# SwiGLU epilogue: 128 packed f32 multiplies converted into scalar pairs (identical results)
# speedup vs baseline: 1.0008x; 1.0008x over previous
.LBB0_264:
	s_lshl_b32 s11, s49, 7
	v_lshrrev_b32_e32 v138, 1, v145
	v_and_or_b32 v138, v138, 24, s11
	s_lshl_b32 s11, s24, 8
	s_add_i32 s11, s11, s44
	s_waitcnt lgkmcnt(0)
	v_mul_f32_e32 v124, v124, v142
	v_mul_f32_e32 v125, v125, v142
	v_or_b32_e32 v145, s11, v146
	v_mul_f32_e32 v146, 0xbfb8aa3b, v124
	v_mul_f32_e32 v147, 0xbfb8aa3b, v125
	v_exp_f32_e32 v146, v146
	v_exp_f32_e32 v147, v147
	v_mul_f32_e32 v120, v120, v142
	v_mul_f32_e32 v121, v121, v142
	v_mul_f32_e32 v122, v122, v142
	v_mul_f32_e32 v123, v123, v142
	v_add_f32_e32 v146, 1.0, v146
	v_add_f32_e32 v147, 1.0, v147
	v_rcp_f32_e32 v146, v146
	v_rcp_f32_e32 v147, v147
	v_mul_f32_e32 v116, v116, v142
	v_mul_f32_e32 v117, v117, v142
	v_mul_f32_e32 v112, v112, v142
	v_mul_f32_e32 v113, v113, v142
	v_mul_f32_e32 v114, v114, v142
	v_mul_f32_e32 v115, v115, v142
	v_mul_f32_e32 v124, v124, v146
	v_mul_f32_e32 v125, v125, v147
	v_or_b32_e32 v138, s45, v138
	v_mul_f32_e32 v120, v120, v124
	v_mul_f32_e32 v121, v121, v125
	v_mul_f32_e32 v124, v126, v142
	v_mul_f32_e32 v125, v127, v142
	v_ashrrev_i32_e32 v139, 31, v138
	v_mul_f32_e32 v126, 0xbfb8aa3b, v124
	v_mul_f32_e32 v127, 0xbfb8aa3b, v125
	v_exp_f32_e32 v126, v126
	v_exp_f32_e32 v127, v127
	s_and_b64 vcc, exec, s[0:1]
	v_add_f32_e32 v126, 1.0, v126
	v_add_f32_e32 v127, 1.0, v127
	v_rcp_f32_e32 v126, v126
	v_rcp_f32_e32 v127, v127
	s_nop 0
	v_mul_f32_e32 v124, v124, v126
	v_mul_f32_e32 v125, v125, v127
	s_nop 0
	v_mul_f32_e32 v122, v122, v124
	v_mul_f32_e32 v123, v123, v125
	v_mul_f32_e32 v124, 0xbfb8aa3b, v116
	v_mul_f32_e32 v125, 0xbfb8aa3b, v117
	v_exp_f32_e32 v124, v124
	v_exp_f32_e32 v125, v125
	v_add_f32_e32 v124, 1.0, v124
	v_add_f32_e32 v125, 1.0, v125
	v_rcp_f32_e32 v124, v124
	v_rcp_f32_e32 v125, v125
	s_nop 0
	v_mul_f32_e32 v116, v116, v124
	v_mul_f32_e32 v117, v117, v125
	s_nop 0
	v_mul_f32_e32 v116, v112, v116
	v_mul_f32_e32 v117, v113, v117
	v_mul_f32_e32 v112, v118, v142
	v_mul_f32_e32 v113, v119, v142
	s_nop 0
	v_mul_f32_e32 v118, 0xbfb8aa3b, v112
	v_mul_f32_e32 v119, 0xbfb8aa3b, v113
	v_exp_f32_e32 v118, v118
	v_exp_f32_e32 v119, v119
	v_add_f32_e32 v118, 1.0, v118
	v_add_f32_e32 v119, 1.0, v119
	v_rcp_f32_e32 v118, v118
	v_rcp_f32_e32 v119, v119
	s_nop 0
	v_mul_f32_e32 v112, v112, v118
	v_mul_f32_e32 v113, v113, v119
	s_nop 0
	v_mul_f32_e32 v118, v114, v112
	v_mul_f32_e32 v119, v115, v113
	v_mul_u32_u24_e32 v150, 0x1600, v145
	v_lshl_add_u32 v150, v138, 1, v150
	v_cvt_pk_bf16_f32 v112, v120, v121
	v_cvt_pk_bf16_f32 v113, v122, v123
	v_cvt_pk_bf16_f32 v114, v116, v117
	v_cvt_pk_bf16_f32 v115, v118, v119
	global_store_dwordx4 v150, v[112:115], s[6:7]
	s_cbranch_vccnz .LBB0_266
	ds_read_b32 v140, v144 offset:64
.LBB0_266:
	s_waitcnt lgkmcnt(0)
	v_mul_f32_e32 v112, v108, v140
	v_mul_f32_e32 v113, v109, v140
	v_mul_f32_e32 v110, v110, v140
	v_mul_f32_e32 v111, v111, v140
	v_mul_f32_e32 v108, 0xbfb8aa3b, v112
	v_exp_f32_e32 v109, v108
	v_mul_f32_e32 v104, v104, v140
	v_mul_f32_e32 v105, v105, v140
	v_mul_f32_e32 v100, v100, v140
	v_mul_f32_e32 v101, v101, v140
	v_mul_f32_e32 v106, v106, v140
	v_mul_f32_e32 v107, v107, v140
	v_add_f32_e32 v109, 1.0, v109
	v_rcp_f32_e32 v114, v109
	v_mul_f32_e32 v109, 0xbfb8aa3b, v113
	v_exp_f32_e32 v109, v109
	v_mul_f32_e32 v96, v96, v140
	v_mul_f32_e32 v97, v97, v140
	v_mul_f32_e32 v98, v98, v140
	v_mul_f32_e32 v99, v99, v140
	v_or_b32_e32 v116, 16, v145
	v_add_f32_e32 v109, 1.0, v109
	v_rcp_f32_e32 v115, v109
	v_mul_f32_e32 v109, 0xbfb8aa3b, v110
	v_exp_f32_e32 v109, v109
	v_mov_b32_e32 v108, 1.0
	v_mul_f32_e32 v112, v112, v114
	v_mul_f32_e32 v113, v113, v115
	s_and_b64 vcc, exec, s[0:1]
	v_add_f32_e32 v109, 1.0, v109
	v_mul_f32_e32 v104, v104, v112
	v_mul_f32_e32 v105, v105, v113
	v_rcp_f32_e32 v112, v109
	v_mul_f32_e32 v109, 0xbfb8aa3b, v111
	v_exp_f32_e32 v109, v109
	s_nop 0
	v_add_f32_e32 v109, 1.0, v109
	v_rcp_f32_e32 v113, v109
	v_mul_f32_e32 v109, 0xbfb8aa3b, v100
	v_exp_f32_e32 v109, v109
	v_mul_f32_e32 v110, v110, v112
	v_mul_f32_e32 v111, v111, v113
	s_nop 0
	v_mul_f32_e32 v106, v106, v110
	v_mul_f32_e32 v107, v107, v111
	v_add_f32_e32 v109, 1.0, v109
	v_rcp_f32_e32 v110, v109
	v_mul_f32_e32 v109, 0xbfb8aa3b, v101
	v_exp_f32_e32 v109, v109
	s_nop 0
	v_add_f32_e32 v109, 1.0, v109
	v_rcp_f32_e32 v111, v109
	s_nop 0
	v_mul_f32_e32 v100, v100, v110
	v_mul_f32_e32 v101, v101, v111
	s_nop 0
	v_mul_f32_e32 v100, v96, v100
	v_mul_f32_e32 v101, v97, v101
	v_mul_f32_e32 v96, v102, v140
	v_mul_f32_e32 v97, v103, v140
	s_nop 0
	v_mul_f32_e32 v102, 0xbfb8aa3b, v96
	v_mul_f32_e32 v103, 0xbfb8aa3b, v97
	v_exp_f32_e32 v102, v102
	v_exp_f32_e32 v103, v103
	v_add_f32_e32 v102, 1.0, v102
	v_add_f32_e32 v103, 1.0, v103
	v_rcp_f32_e32 v102, v102
	v_rcp_f32_e32 v103, v103
	s_nop 0
	v_mul_f32_e32 v96, v96, v102
	v_mul_f32_e32 v97, v97, v103
	s_nop 0
	v_mul_f32_e32 v102, v98, v96
	v_mul_f32_e32 v103, v99, v97
	v_add_u32_e32 v150, 0x16000, v150
	v_cvt_pk_bf16_f32 v96, v104, v105
	v_cvt_pk_bf16_f32 v97, v106, v107
	v_cvt_pk_bf16_f32 v98, v100, v101
	v_cvt_pk_bf16_f32 v99, v102, v103
	global_store_dwordx4 v150, v[96:99], s[6:7]
	s_nop 1
	v_mov_b32_e32 v96, 1.0
	s_cbranch_vccnz .LBB0_268
	ds_read_b32 v96, v144 offset:128
.LBB0_268:
	v_or_b32_e32 v97, 32, v145
	s_waitcnt lgkmcnt(0)
	v_mul_f32_e32 v92, v92, v96
	v_mul_f32_e32 v93, v93, v96
	v_mul_f32_e32 v88, v88, v96
	v_mul_f32_e32 v89, v89, v96
	v_mul_f32_e32 v98, 0xbfb8aa3b, v92
	v_mul_f32_e32 v99, 0xbfb8aa3b, v93
	v_exp_f32_e32 v98, v98
	v_exp_f32_e32 v99, v99
	v_mul_f32_e32 v90, v90, v96
	v_mul_f32_e32 v91, v91, v96
	v_mul_f32_e32 v84, v84, v96
	v_mul_f32_e32 v85, v85, v96
	v_add_f32_e32 v98, 1.0, v98
	v_add_f32_e32 v99, 1.0, v99
	v_rcp_f32_e32 v98, v98
	v_rcp_f32_e32 v99, v99
	v_mul_f32_e32 v80, v80, v96
	v_mul_f32_e32 v81, v81, v96
	v_mul_f32_e32 v82, v82, v96
	v_mul_f32_e32 v83, v83, v96
	s_and_b64 vcc, exec, s[0:1]
	v_mul_f32_e32 v92, v92, v98
	v_mul_f32_e32 v93, v93, v99
	s_nop 0
	v_mul_f32_e32 v88, v88, v92
	v_mul_f32_e32 v89, v89, v93
	v_mul_f32_e32 v92, v94, v96
	v_mul_f32_e32 v93, v95, v96
	s_nop 0
	v_mul_f32_e32 v94, 0xbfb8aa3b, v92
	v_mul_f32_e32 v95, 0xbfb8aa3b, v93
	v_exp_f32_e32 v94, v94
	v_exp_f32_e32 v95, v95
	v_add_f32_e32 v94, 1.0, v94
	v_add_f32_e32 v95, 1.0, v95
	v_rcp_f32_e32 v94, v94
	v_rcp_f32_e32 v95, v95
	s_nop 0
	v_mul_f32_e32 v92, v92, v94
	v_mul_f32_e32 v93, v93, v95
	s_nop 0
	v_mul_f32_e32 v90, v90, v92
	v_mul_f32_e32 v91, v91, v93
	v_mul_f32_e32 v92, 0xbfb8aa3b, v84
	v_mul_f32_e32 v93, 0xbfb8aa3b, v85
	v_exp_f32_e32 v92, v92
	v_exp_f32_e32 v93, v93
	v_add_f32_e32 v92, 1.0, v92
	v_add_f32_e32 v93, 1.0, v93
	v_rcp_f32_e32 v92, v92
	v_rcp_f32_e32 v93, v93
	s_nop 0
	v_mul_f32_e32 v84, v84, v92
	v_mul_f32_e32 v85, v85, v93
	s_nop 0
	v_mul_f32_e32 v84, v80, v84
	v_mul_f32_e32 v85, v81, v85
	v_mul_f32_e32 v80, v86, v96
	v_mul_f32_e32 v81, v87, v96
	s_nop 0
	v_mul_f32_e32 v86, 0xbfb8aa3b, v80
	v_mul_f32_e32 v87, 0xbfb8aa3b, v81
	v_exp_f32_e32 v86, v86
	v_exp_f32_e32 v87, v87
	v_add_f32_e32 v86, 1.0, v86
	v_add_f32_e32 v87, 1.0, v87
	v_rcp_f32_e32 v86, v86
	v_rcp_f32_e32 v87, v87
	s_nop 0
	v_mul_f32_e32 v80, v80, v86
	v_mul_f32_e32 v81, v81, v87
	s_nop 0
	v_mul_f32_e32 v86, v82, v80
	v_mul_f32_e32 v87, v83, v81
	v_add_u32_e32 v150, 0x16000, v150
	v_cvt_pk_bf16_f32 v80, v88, v89
	v_cvt_pk_bf16_f32 v81, v90, v91
	v_cvt_pk_bf16_f32 v82, v84, v85
	v_cvt_pk_bf16_f32 v83, v86, v87
	global_store_dwordx4 v150, v[80:83], s[6:7]
	s_cbranch_vccnz .LBB0_270
	ds_read_b32 v108, v144 offset:192
.LBB0_270:
	s_waitcnt lgkmcnt(0)
	v_mul_f32_e32 v80, v76, v108
	v_mul_f32_e32 v81, v77, v108
	v_mul_f32_e32 v78, v78, v108
	v_mul_f32_e32 v79, v79, v108
	v_mul_f32_e32 v76, 0xbfb8aa3b, v80
	v_exp_f32_e32 v77, v76
	v_mul_f32_e32 v72, v72, v108
	v_mul_f32_e32 v73, v73, v108
	v_mul_f32_e32 v68, v68, v108
	v_mul_f32_e32 v69, v69, v108
	v_mul_f32_e32 v74, v74, v108
	v_mul_f32_e32 v75, v75, v108
	v_add_f32_e32 v77, 1.0, v77
	v_rcp_f32_e32 v82, v77
	v_mul_f32_e32 v77, 0xbfb8aa3b, v81
	v_exp_f32_e32 v77, v77
	v_mul_f32_e32 v64, v64, v108
	v_mul_f32_e32 v65, v65, v108
	v_mul_f32_e32 v66, v66, v108
	v_mul_f32_e32 v67, v67, v108
	v_or_b32_e32 v84, 48, v145
	v_add_f32_e32 v77, 1.0, v77
	v_rcp_f32_e32 v83, v77
	v_mul_f32_e32 v77, 0xbfb8aa3b, v78
	v_exp_f32_e32 v77, v77
	v_mov_b32_e32 v76, 1.0
	v_mul_f32_e32 v80, v80, v82
	v_mul_f32_e32 v81, v81, v83
	s_and_b64 vcc, exec, s[0:1]
	v_add_f32_e32 v77, 1.0, v77
	v_mul_f32_e32 v72, v72, v80
	v_mul_f32_e32 v73, v73, v81
	v_rcp_f32_e32 v80, v77
	v_mul_f32_e32 v77, 0xbfb8aa3b, v79
	v_exp_f32_e32 v77, v77
	s_nop 0
	v_add_f32_e32 v77, 1.0, v77
	v_rcp_f32_e32 v81, v77
	v_mul_f32_e32 v77, 0xbfb8aa3b, v68
	v_exp_f32_e32 v77, v77
	v_mul_f32_e32 v78, v78, v80
	v_mul_f32_e32 v79, v79, v81
	s_nop 0
	v_mul_f32_e32 v74, v74, v78
	v_mul_f32_e32 v75, v75, v79
	v_add_f32_e32 v77, 1.0, v77
	v_rcp_f32_e32 v78, v77
	v_mul_f32_e32 v77, 0xbfb8aa3b, v69
	v_exp_f32_e32 v77, v77
	s_nop 0
	v_add_f32_e32 v77, 1.0, v77
	v_rcp_f32_e32 v79, v77
	s_nop 0
	v_mul_f32_e32 v68, v68, v78
	v_mul_f32_e32 v69, v69, v79
	s_nop 0
	v_mul_f32_e32 v68, v64, v68
	v_mul_f32_e32 v69, v65, v69
	v_mul_f32_e32 v64, v70, v108
	v_mul_f32_e32 v65, v71, v108
	s_nop 0
	v_mul_f32_e32 v70, 0xbfb8aa3b, v64
	v_mul_f32_e32 v71, 0xbfb8aa3b, v65
	v_exp_f32_e32 v70, v70
	v_exp_f32_e32 v71, v71
	v_add_f32_e32 v70, 1.0, v70
	v_add_f32_e32 v71, 1.0, v71
	v_rcp_f32_e32 v70, v70
	v_rcp_f32_e32 v71, v71
	s_nop 0
	v_mul_f32_e32 v64, v64, v70
	v_mul_f32_e32 v65, v65, v71
	s_nop 0
	v_mul_f32_e32 v70, v66, v64
	v_mul_f32_e32 v71, v67, v65
	v_add_u32_e32 v150, 0x16000, v150
	v_cvt_pk_bf16_f32 v64, v72, v73
	v_cvt_pk_bf16_f32 v65, v74, v75
	v_cvt_pk_bf16_f32 v66, v68, v69
	v_cvt_pk_bf16_f32 v67, v70, v71
	global_store_dwordx4 v150, v[64:67], s[6:7]
	s_nop 1
	v_mov_b32_e32 v64, 1.0
	s_cbranch_vccnz .LBB0_272
	ds_read_b32 v64, v144 offset:512
.LBB0_272:
	v_add_u32_e32 v65, 0x80, v145
	s_waitcnt lgkmcnt(0)
	v_mul_f32_e32 v60, v60, v64
	v_mul_f32_e32 v61, v61, v64
	v_mul_f32_e32 v56, v56, v64
	v_mul_f32_e32 v57, v57, v64
	v_mul_f32_e32 v66, 0xbfb8aa3b, v60
	v_mul_f32_e32 v67, 0xbfb8aa3b, v61
	v_exp_f32_e32 v66, v66
	v_exp_f32_e32 v67, v67
	v_mul_f32_e32 v58, v58, v64
	v_mul_f32_e32 v59, v59, v64
	v_mul_f32_e32 v52, v52, v64
	v_mul_f32_e32 v53, v53, v64
	v_add_f32_e32 v66, 1.0, v66
	v_add_f32_e32 v67, 1.0, v67
	v_rcp_f32_e32 v66, v66
	v_rcp_f32_e32 v67, v67
	v_mul_f32_e32 v48, v48, v64
	v_mul_f32_e32 v49, v49, v64
	v_mul_f32_e32 v50, v50, v64
	v_mul_f32_e32 v51, v51, v64
	s_and_b64 vcc, exec, s[0:1]
	v_mul_f32_e32 v60, v60, v66
	v_mul_f32_e32 v61, v61, v67
	s_nop 0
	v_mul_f32_e32 v56, v56, v60
	v_mul_f32_e32 v57, v57, v61
	v_mul_f32_e32 v60, v62, v64
	v_mul_f32_e32 v61, v63, v64
	s_nop 0
	v_mul_f32_e32 v62, 0xbfb8aa3b, v60
	v_mul_f32_e32 v63, 0xbfb8aa3b, v61
	v_exp_f32_e32 v62, v62
	v_exp_f32_e32 v63, v63
	v_add_f32_e32 v62, 1.0, v62
	v_add_f32_e32 v63, 1.0, v63
	v_rcp_f32_e32 v62, v62
	v_rcp_f32_e32 v63, v63
	s_nop 0
	v_mul_f32_e32 v60, v60, v62
	v_mul_f32_e32 v61, v61, v63
	s_nop 0
	v_mul_f32_e32 v58, v58, v60
	v_mul_f32_e32 v59, v59, v61
	v_mul_f32_e32 v60, 0xbfb8aa3b, v52
	v_mul_f32_e32 v61, 0xbfb8aa3b, v53
	v_exp_f32_e32 v60, v60
	v_exp_f32_e32 v61, v61
	v_add_f32_e32 v60, 1.0, v60
	v_add_f32_e32 v61, 1.0, v61
	v_rcp_f32_e32 v60, v60
	v_rcp_f32_e32 v61, v61
	s_nop 0
	v_mul_f32_e32 v52, v52, v60
	v_mul_f32_e32 v53, v53, v61
	s_nop 0
	v_mul_f32_e32 v52, v48, v52
	v_mul_f32_e32 v53, v49, v53
	v_mul_f32_e32 v48, v54, v64
	v_mul_f32_e32 v49, v55, v64
	s_nop 0
	v_mul_f32_e32 v54, 0xbfb8aa3b, v48
	v_mul_f32_e32 v55, 0xbfb8aa3b, v49
	v_exp_f32_e32 v54, v54
	v_exp_f32_e32 v55, v55
	v_add_f32_e32 v54, 1.0, v54
	v_add_f32_e32 v55, 1.0, v55
	v_rcp_f32_e32 v54, v54
	v_rcp_f32_e32 v55, v55
	s_nop 0
	v_mul_f32_e32 v48, v48, v54
	v_mul_f32_e32 v49, v49, v55
	s_nop 0
	v_mul_f32_e32 v54, v50, v48
	v_mul_f32_e32 v55, v51, v49
	v_add_u32_e32 v150, 0x6e000, v150
	v_cvt_pk_bf16_f32 v48, v56, v57
	v_cvt_pk_bf16_f32 v49, v58, v59
	v_cvt_pk_bf16_f32 v50, v52, v53
	v_cvt_pk_bf16_f32 v51, v54, v55
	global_store_dwordx4 v150, v[48:51], s[6:7]
	s_cbranch_vccnz .LBB0_274
	ds_read_b32 v76, v144 offset:576
.LBB0_274:
	s_waitcnt lgkmcnt(0)
	v_mul_f32_e32 v48, v44, v76
	v_mul_f32_e32 v49, v45, v76
	v_mul_f32_e32 v46, v46, v76
	v_mul_f32_e32 v47, v47, v76
	v_mul_f32_e32 v44, 0xbfb8aa3b, v48
	v_exp_f32_e32 v45, v44
	v_mul_f32_e32 v40, v40, v76
	v_mul_f32_e32 v41, v41, v76
	v_mul_f32_e32 v36, v36, v76
	v_mul_f32_e32 v37, v37, v76
	v_mul_f32_e32 v42, v42, v76
	v_mul_f32_e32 v43, v43, v76
	v_add_f32_e32 v45, 1.0, v45
	v_rcp_f32_e32 v50, v45
	v_mul_f32_e32 v45, 0xbfb8aa3b, v49
	v_exp_f32_e32 v45, v45
	v_mul_f32_e32 v32, v32, v76
	v_mul_f32_e32 v33, v33, v76
	v_mul_f32_e32 v34, v34, v76
	v_mul_f32_e32 v35, v35, v76
	v_add_u32_e32 v52, 0x90, v145
	v_add_f32_e32 v45, 1.0, v45
	v_rcp_f32_e32 v51, v45
	v_mul_f32_e32 v45, 0xbfb8aa3b, v46
	v_exp_f32_e32 v45, v45
	v_mov_b32_e32 v44, 1.0
	v_mul_f32_e32 v48, v48, v50
	v_mul_f32_e32 v49, v49, v51
	s_and_b64 vcc, exec, s[0:1]
	v_add_f32_e32 v45, 1.0, v45
	v_mul_f32_e32 v40, v40, v48
	v_mul_f32_e32 v41, v41, v49
	v_rcp_f32_e32 v48, v45
	v_mul_f32_e32 v45, 0xbfb8aa3b, v47
	v_exp_f32_e32 v45, v45
	s_nop 0
	v_add_f32_e32 v45, 1.0, v45
	v_rcp_f32_e32 v49, v45
	v_mul_f32_e32 v45, 0xbfb8aa3b, v36
	v_exp_f32_e32 v45, v45
	v_mul_f32_e32 v46, v46, v48
	v_mul_f32_e32 v47, v47, v49
	s_nop 0
	v_mul_f32_e32 v42, v42, v46
	v_mul_f32_e32 v43, v43, v47
	v_add_f32_e32 v45, 1.0, v45
	v_rcp_f32_e32 v46, v45
	v_mul_f32_e32 v45, 0xbfb8aa3b, v37
	v_exp_f32_e32 v45, v45
	s_nop 0
	v_add_f32_e32 v45, 1.0, v45
	v_rcp_f32_e32 v47, v45
	s_nop 0
	v_mul_f32_e32 v36, v36, v46
	v_mul_f32_e32 v37, v37, v47
	s_nop 0
	v_mul_f32_e32 v36, v32, v36
	v_mul_f32_e32 v37, v33, v37
	v_mul_f32_e32 v32, v38, v76
	v_mul_f32_e32 v33, v39, v76
	s_nop 0
	v_mul_f32_e32 v38, 0xbfb8aa3b, v32
	v_mul_f32_e32 v39, 0xbfb8aa3b, v33
	v_exp_f32_e32 v38, v38
	v_exp_f32_e32 v39, v39
	v_add_f32_e32 v38, 1.0, v38
	v_add_f32_e32 v39, 1.0, v39
	v_rcp_f32_e32 v38, v38
	v_rcp_f32_e32 v39, v39
	s_nop 0
	v_mul_f32_e32 v32, v32, v38
	v_mul_f32_e32 v33, v33, v39
	s_nop 0
	v_mul_f32_e32 v38, v34, v32
	v_mul_f32_e32 v39, v35, v33
	v_add_u32_e32 v150, 0x16000, v150
	v_cvt_pk_bf16_f32 v32, v40, v41
	v_cvt_pk_bf16_f32 v33, v42, v43
	v_cvt_pk_bf16_f32 v34, v36, v37
	v_cvt_pk_bf16_f32 v35, v38, v39
	global_store_dwordx4 v150, v[32:35], s[6:7]
	s_nop 1
	v_mov_b32_e32 v32, 1.0
	s_cbranch_vccnz .LBB0_276
	ds_read_b32 v32, v144 offset:640
.LBB0_276:
	v_add_u32_e32 v33, 0xa0, v145
	s_waitcnt lgkmcnt(0)
	v_mul_f32_e32 v28, v28, v32
	v_mul_f32_e32 v29, v29, v32
	v_mul_f32_e32 v24, v24, v32
	v_mul_f32_e32 v25, v25, v32
	v_mul_f32_e32 v34, 0xbfb8aa3b, v28
	v_mul_f32_e32 v35, 0xbfb8aa3b, v29
	v_exp_f32_e32 v34, v34
	v_exp_f32_e32 v35, v35
	v_mul_f32_e32 v26, v26, v32
	v_mul_f32_e32 v27, v27, v32
	v_mul_f32_e32 v20, v20, v32
	v_mul_f32_e32 v21, v21, v32
	v_add_f32_e32 v34, 1.0, v34
	v_add_f32_e32 v35, 1.0, v35
	v_rcp_f32_e32 v34, v34
	v_rcp_f32_e32 v35, v35
	v_mul_f32_e32 v16, v16, v32
	v_mul_f32_e32 v17, v17, v32
	v_mul_f32_e32 v18, v18, v32
	v_mul_f32_e32 v19, v19, v32
	s_and_b64 vcc, exec, s[0:1]
	v_mul_f32_e32 v28, v28, v34
	v_mul_f32_e32 v29, v29, v35
	s_nop 0
	v_mul_f32_e32 v24, v24, v28
	v_mul_f32_e32 v25, v25, v29
	v_mul_f32_e32 v28, v30, v32
	v_mul_f32_e32 v29, v31, v32
	s_nop 0
	v_mul_f32_e32 v30, 0xbfb8aa3b, v28
	v_mul_f32_e32 v31, 0xbfb8aa3b, v29
	v_exp_f32_e32 v30, v30
	v_exp_f32_e32 v31, v31
	v_add_f32_e32 v30, 1.0, v30
	v_add_f32_e32 v31, 1.0, v31
	v_rcp_f32_e32 v30, v30
	v_rcp_f32_e32 v31, v31
	s_nop 0
	v_mul_f32_e32 v28, v28, v30
	v_mul_f32_e32 v29, v29, v31
	s_nop 0
	v_mul_f32_e32 v26, v26, v28
	v_mul_f32_e32 v27, v27, v29
	v_mul_f32_e32 v28, 0xbfb8aa3b, v20
	v_mul_f32_e32 v29, 0xbfb8aa3b, v21
	v_exp_f32_e32 v28, v28
	v_exp_f32_e32 v29, v29
	v_add_f32_e32 v28, 1.0, v28
	v_add_f32_e32 v29, 1.0, v29
	v_rcp_f32_e32 v28, v28
	v_rcp_f32_e32 v29, v29
	s_nop 0
	v_mul_f32_e32 v20, v20, v28
	v_mul_f32_e32 v21, v21, v29
	s_nop 0
	v_mul_f32_e32 v20, v16, v20
	v_mul_f32_e32 v21, v17, v21
	v_mul_f32_e32 v16, v22, v32
	v_mul_f32_e32 v17, v23, v32
	s_nop 0
	v_mul_f32_e32 v22, 0xbfb8aa3b, v16
	v_mul_f32_e32 v23, 0xbfb8aa3b, v17
	v_exp_f32_e32 v22, v22
	v_exp_f32_e32 v23, v23
	v_add_f32_e32 v22, 1.0, v22
	v_add_f32_e32 v23, 1.0, v23
	v_rcp_f32_e32 v22, v22
	v_rcp_f32_e32 v23, v23
	s_nop 0
	v_mul_f32_e32 v16, v16, v22
	v_mul_f32_e32 v17, v17, v23
	s_nop 0
	v_mul_f32_e32 v22, v18, v16
	v_mul_f32_e32 v23, v19, v17
	v_add_u32_e32 v150, 0x16000, v150
	v_cvt_pk_bf16_f32 v16, v24, v25
	v_cvt_pk_bf16_f32 v17, v26, v27
	v_cvt_pk_bf16_f32 v18, v20, v21
	v_cvt_pk_bf16_f32 v19, v22, v23
	global_store_dwordx4 v150, v[16:19], s[6:7]
	s_cbranch_vccnz .LBB0_278
	ds_read_b32 v44, v144 offset:704
.LBB0_278:
	s_waitcnt lgkmcnt(0)
	v_mul_f32_e32 v12, v12, v44
	v_mul_f32_e32 v13, v13, v44
	v_mul_f32_e32 v8, v8, v44
	v_mul_f32_e32 v9, v9, v44
	v_mul_f32_e32 v16, 0xbfb8aa3b, v12
	v_mul_f32_e32 v17, 0xbfb8aa3b, v13
	v_exp_f32_e32 v16, v16
	v_exp_f32_e32 v17, v17
	v_mul_f32_e32 v10, v10, v44
	v_mul_f32_e32 v11, v11, v44
	v_mul_f32_e32 v4, v4, v44
	v_mul_f32_e32 v5, v5, v44
	v_add_f32_e32 v16, 1.0, v16
	v_add_f32_e32 v17, 1.0, v17
	v_rcp_f32_e32 v16, v16
	v_rcp_f32_e32 v17, v17
	v_mul_f32_e32 v0, v0, v44
	v_mul_f32_e32 v1, v1, v44
	v_mul_f32_e32 v2, v2, v44
	v_mul_f32_e32 v3, v3, v44
	v_add_u32_e32 v18, 0xb0, v145
	v_mul_f32_e32 v12, v12, v16
	v_mul_f32_e32 v13, v13, v17
	s_andn2_b64 vcc, exec, s[4:5]
	v_mul_f32_e32 v8, v8, v12
	v_mul_f32_e32 v9, v9, v13
	v_mul_f32_e32 v12, v14, v44
	v_mul_f32_e32 v13, v15, v44
	s_nop 0
	v_mul_f32_e32 v14, 0xbfb8aa3b, v12
	v_mul_f32_e32 v15, 0xbfb8aa3b, v13
	v_exp_f32_e32 v14, v14
	v_exp_f32_e32 v15, v15
	v_add_f32_e32 v14, 1.0, v14
	v_add_f32_e32 v15, 1.0, v15
	v_rcp_f32_e32 v14, v14
	v_rcp_f32_e32 v15, v15
	s_nop 0
	v_mul_f32_e32 v12, v12, v14
	v_mul_f32_e32 v13, v13, v15
	s_nop 0
	v_mul_f32_e32 v10, v10, v12
	v_mul_f32_e32 v11, v11, v13
	v_mul_f32_e32 v12, 0xbfb8aa3b, v4
	v_mul_f32_e32 v13, 0xbfb8aa3b, v5
	v_exp_f32_e32 v12, v12
	v_exp_f32_e32 v13, v13
	v_add_f32_e32 v12, 1.0, v12
	v_add_f32_e32 v13, 1.0, v13
	v_rcp_f32_e32 v12, v12
	v_rcp_f32_e32 v13, v13
	s_nop 0
	v_mul_f32_e32 v4, v4, v12
	v_mul_f32_e32 v5, v5, v13
	s_nop 0
	v_mul_f32_e32 v4, v0, v4
	v_mul_f32_e32 v5, v1, v5
	v_mul_f32_e32 v0, v6, v44
	v_mul_f32_e32 v1, v7, v44
	s_nop 0
	v_mul_f32_e32 v6, 0xbfb8aa3b, v0
	v_mul_f32_e32 v7, 0xbfb8aa3b, v1
	v_exp_f32_e32 v6, v6
	v_exp_f32_e32 v7, v7
	v_add_f32_e32 v6, 1.0, v6
	v_add_f32_e32 v7, 1.0, v7
	v_rcp_f32_e32 v6, v6
	v_rcp_f32_e32 v7, v7
	s_nop 0
	v_mul_f32_e32 v0, v0, v6
	v_mul_f32_e32 v1, v1, v7
	s_nop 0
	v_mul_f32_e32 v6, v2, v0
	v_mul_f32_e32 v7, v3, v1
	v_add_u32_e32 v150, 0x16000, v150
	v_cvt_pk_bf16_f32 v0, v8, v9
	v_cvt_pk_bf16_f32 v1, v10, v11
	v_cvt_pk_bf16_f32 v2, v4, v5
	v_cvt_pk_bf16_f32 v3, v6, v7
	s_mov_b64 s[0:1], -1
	global_store_dwordx4 v150, v[0:3], s[6:7]
	s_cbranch_vccnz .LBB0_249
	s_andn2_b64 vcc, exec, s[2:3]
	s_cbranch_vccnz .LBB0_248
	s_barrier
	s_branch .LBB0_248
